# speedup vs baseline: 1.0041x; 1.0041x over previous
; __device__ __forceinline__ f32x4 mfma16(bf16x8 a, bf16x8 b, f32x4 c) { return __builtin_amdgcn_mfma_f32_16x16x32_bf16(a, b, c, 0, 0, 0); }
; __device__ __forceinline__ void spatial_phase(unsigned char* lds, const Params& p, int vb, int G, bool dry) {
;     ...
;         f32x4 acc[2][8];
; #pragma unroll
;         for (int v = 0; v < 2; ++v)
; #pragma unroll
;             for (int tb = 0; tb < 8; ++tb) acc[v][tb] = (f32x4){0.f, 0.f, 0.f, 0.f};
; #pragma unroll
;         for (int ks = 0; ks < 4; ++ks) { bf16x8 af[2];
; #pragma unroll
;             for (int v = 0; v < 2; ++v) af[v] = *(const bf16x8*)(vTl + (16 * (2 * wave + v) + li) * 136 + 32 * ks + 8 * fq);
; #pragma unroll
;             for (int tb = 0; tb < 8; ++tb) { const bf16x8 bf_ = *(const bf16x8*)(Wl + (16 * tb + li) * 136 + 32 * ks + 8 * fq); acc[0][tb] = mfma16(af[0], bf_, acc[0][tb]); acc[1][tb] = mfma16(af[1], bf_, acc[1][tb]); } }
.LBB0_1586:
.LBB0_1587:
	s_waitcnt lgkmcnt(0)
	s_barrier
	ds_read_b128 v[34:37], v161 offset:34816
	ds_read_b128 v[38:41], v161 offset:39168
	ds_read_b128 v[42:45], v162
	ds_read_b128 v[50:53], v162 offset:4352
	ds_read_b128 v[58:61], v162 offset:8704
	ds_read_b128 v[66:69], v162 offset:13056
	ds_read_b128 v[74:77], v162 offset:17408
	ds_read_b128 v[82:85], v162 offset:21760
	ds_read_b128 v[90:93], v162 offset:26112
	ds_read_b128 v[168:171], v162 offset:30464
	s_waitcnt lgkmcnt(7)
	v_mfma_f32_16x16x32_bf16 v[46:49], v[34:37], v[42:45], 0
	s_lshl_b32 s4, s58, 9
	s_and_b32 s20, s4, 0xe00
	v_lshl_add_u64 v[132:133], v[128:129], 0, s[20:21]
	v_mfma_f32_16x16x32_bf16 v[42:45], v[38:41], v[42:45], 0
	v_readlane_b32 s40, v251, 2
	s_lshl_b64 s[4:5], s[38:39], 1
	v_lshl_or_b32 v0, v134, 2, s20
	s_waitcnt lgkmcnt(6)
	v_mfma_f32_16x16x32_bf16 v[54:57], v[34:37], v[50:53], 0
	v_readlane_b32 s41, v251, 3
	v_cmp_gt_u32_e32 vcc, s63, v145
	v_readlane_b32 s42, v251, 4
	v_mfma_f32_16x16x32_bf16 v[50:53], v[38:41], v[50:53], 0
	v_readlane_b32 s43, v251, 5
	v_readlane_b32 s44, v251, 6
	v_readlane_b32 s45, v251, 7
	s_waitcnt lgkmcnt(5)
	v_mfma_f32_16x16x32_bf16 v[62:65], v[34:37], v[58:61], 0
	v_readlane_b32 s46, v251, 8
	v_readlane_b32 s47, v251, 9
	v_readlane_b32 s48, v251, 10
	v_mfma_f32_16x16x32_bf16 v[58:61], v[38:41], v[58:61], 0
	v_readlane_b32 s49, v251, 11
	v_readlane_b32 s50, v251, 12
	v_readlane_b32 s51, v251, 13
	s_waitcnt lgkmcnt(4)
	v_mfma_f32_16x16x32_bf16 v[70:73], v[34:37], v[66:69], 0
	v_readlane_b32 s52, v251, 14
	v_readlane_b32 s53, v251, 15
	v_readlane_b32 s54, v251, 16
	v_mfma_f32_16x16x32_bf16 v[66:69], v[38:41], v[66:69], 0
	v_readlane_b32 s55, v251, 17
	s_waitcnt lgkmcnt(3)
	v_mfma_f32_16x16x32_bf16 v[78:81], v[34:37], v[74:77], 0
	v_mfma_f32_16x16x32_bf16 v[74:77], v[38:41], v[74:77], 0
	s_waitcnt lgkmcnt(2)
	v_mfma_f32_16x16x32_bf16 v[86:89], v[34:37], v[82:85], 0
	v_mfma_f32_16x16x32_bf16 v[82:85], v[38:41], v[82:85], 0
	s_waitcnt lgkmcnt(1)
	v_mfma_f32_16x16x32_bf16 v[164:167], v[34:37], v[90:93], 0
	v_mfma_f32_16x16x32_bf16 v[90:93], v[38:41], v[90:93], 0
	s_waitcnt lgkmcnt(0)
	v_mfma_f32_16x16x32_bf16 v[34:37], v[34:37], v[168:171], 0
	v_mfma_f32_16x16x32_bf16 v[38:41], v[38:41], v[168:171], 0
	ds_read_b128 v[168:171], v161 offset:34880
	ds_read_b128 v[172:175], v161 offset:39232
	ds_read_b128 v[176:179], v162 offset:64
	s_waitcnt lgkmcnt(0)
	v_mfma_f32_16x16x32_bf16 v[46:49], v[168:171], v[176:179], v[46:49]
	v_mfma_f32_16x16x32_bf16 v[42:45], v[172:175], v[176:179], v[42:45]
	ds_read_b128 v[176:179], v162 offset:4416
	s_waitcnt lgkmcnt(0)
	v_mfma_f32_16x16x32_bf16 v[54:57], v[168:171], v[176:179], v[54:57]
	v_mfma_f32_16x16x32_bf16 v[50:53], v[172:175], v[176:179], v[50:53]
	ds_read_b128 v[176:179], v162 offset:8768
	s_waitcnt lgkmcnt(0)
	v_mfma_f32_16x16x32_bf16 v[62:65], v[168:171], v[176:179], v[62:65]
	v_mfma_f32_16x16x32_bf16 v[58:61], v[172:175], v[176:179], v[58:61]
	ds_read_b128 v[176:179], v162 offset:13120
	s_waitcnt lgkmcnt(0)
	v_mfma_f32_16x16x32_bf16 v[70:73], v[168:171], v[176:179], v[70:73]
	v_mfma_f32_16x16x32_bf16 v[66:69], v[172:175], v[176:179], v[66:69]
	ds_read_b128 v[176:179], v162 offset:17472
	s_waitcnt lgkmcnt(0)
	v_mfma_f32_16x16x32_bf16 v[78:81], v[168:171], v[176:179], v[78:81]
	v_mfma_f32_16x16x32_bf16 v[74:77], v[172:175], v[176:179], v[74:77]
	ds_read_b128 v[176:179], v162 offset:21824
	s_waitcnt lgkmcnt(0)
	v_mfma_f32_16x16x32_bf16 v[86:89], v[168:171], v[176:179], v[86:89]
	v_mfma_f32_16x16x32_bf16 v[82:85], v[172:175], v[176:179], v[82:85]
	ds_read_b128 v[176:179], v162 offset:26176
	s_waitcnt lgkmcnt(0)
	v_mfma_f32_16x16x32_bf16 v[164:167], v[168:171], v[176:179], v[164:167]
	v_mfma_f32_16x16x32_bf16 v[90:93], v[172:175], v[176:179], v[90:93]
	ds_read_b128 v[176:179], v162 offset:30528
	s_waitcnt lgkmcnt(0)
	v_mfma_f32_16x16x32_bf16 v[34:37], v[168:171], v[176:179], v[34:37]
	v_mfma_f32_16x16x32_bf16 v[38:41], v[172:175], v[176:179], v[38:41]
	ds_read_b128 v[168:171], v161 offset:34944
	ds_read_b128 v[172:175], v161 offset:39296
	ds_read_b128 v[176:179], v162 offset:128
	s_waitcnt lgkmcnt(0)
	v_mfma_f32_16x16x32_bf16 v[46:49], v[168:171], v[176:179], v[46:49]
	v_mfma_f32_16x16x32_bf16 v[42:45], v[172:175], v[176:179], v[42:45]
	ds_read_b128 v[176:179], v162 offset:4480
	s_waitcnt lgkmcnt(0)
	v_mfma_f32_16x16x32_bf16 v[54:57], v[168:171], v[176:179], v[54:57]
	v_mfma_f32_16x16x32_bf16 v[50:53], v[172:175], v[176:179], v[50:53]
	ds_read_b128 v[176:179], v162 offset:8832
	s_waitcnt lgkmcnt(0)
	v_mfma_f32_16x16x32_bf16 v[62:65], v[168:171], v[176:179], v[62:65]
	v_mfma_f32_16x16x32_bf16 v[58:61], v[172:175], v[176:179], v[58:61]
	ds_read_b128 v[176:179], v162 offset:13184
	s_waitcnt lgkmcnt(0)
	v_mfma_f32_16x16x32_bf16 v[70:73], v[168:171], v[176:179], v[70:73]
	v_mfma_f32_16x16x32_bf16 v[66:69], v[172:175], v[176:179], v[66:69]
	ds_read_b128 v[176:179], v162 offset:17536
	s_waitcnt lgkmcnt(0)
	v_mfma_f32_16x16x32_bf16 v[180:183], v[168:171], v[176:179], v[78:81]
	v_mfma_f32_16x16x32_bf16 v[176:179], v[172:175], v[176:179], v[74:77]
	s_nop 2
	ds_read_b128 v[74:77], v162 offset:21888
	s_waitcnt lgkmcnt(0)
	v_mfma_f32_16x16x32_bf16 v[184:187], v[168:171], v[74:77], v[86:89]
	v_mfma_f32_16x16x32_bf16 v[188:191], v[172:175], v[74:77], v[82:85]
	ds_read_b128 v[74:77], v162 offset:26240
	s_waitcnt lgkmcnt(0)
	v_mfma_f32_16x16x32_bf16 v[164:167], v[168:171], v[74:77], v[164:167]
	v_mfma_f32_16x16x32_bf16 v[192:195], v[172:175], v[74:77], v[90:93]
	ds_read_b128 v[74:77], v162 offset:30592
	s_waitcnt lgkmcnt(0)
; __device__ __forceinline__ unsigned cvt_pk(float lo, float hi) { unsigned r; asm("v_cvt_pk_bf16_f32 %0, %1, %2" : "=v"(r) : "v"(lo), "v"(hi)); return r; }
; __device__ __forceinline__ float bflo(unsigned w) { return __uint_as_float(w << 16); }
; __device__ __forceinline__ float bfhi(unsigned w) { return __uint_as_float(w & 0xffff0000u); }
; __device__ __forceinline__ f32x4 mfma16(bf16x8 a, bf16x8 b, f32x4 c) { return __builtin_amdgcn_mfma_f32_16x16x32_bf16(a, b, c, 0, 0, 0); }
; __device__ __forceinline__ void spatial_phase(unsigned char* lds, const Params& p, int vb, int G, bool dry) {
;     ...
;             for (int tb = 0; tb < 8; ++tb) { const bf16x8 bf_ = *(const bf16x8*)(Wl + (16 * tb + li) * 136 + 32 * ks + 8 * fq); acc[0][tb] = mfma16(af[0], bf_, acc[0][tb]); acc[1][tb] = mfma16(af[1], bf_, acc[1][tb]); } }
; #pragma unroll
;         for (int tb = 0; tb < 8; ++tb) { const int t = 16 * tb + li;
;             if (t < L && !dry) { const float bs = p.in[16][g * 128 + t];
; #pragma unroll
;                 for (int v = 0; v < 2; ++v) { bf16_t* up = U + (size_t)(row0 + t) * D + g * 256 + 16 * (2 * wave + v) + 4 * fq; const u32x2 uw = *(const u32x2*)up;
;                     u32x2 w; w.x = cvt_pk(bflo(uw.x) * (acc[v][tb][0] + bs), bfhi(uw.x) * (acc[v][tb][1] + bs)); w.y = cvt_pk(bflo(uw.y) * (acc[v][tb][2] + bs), bfhi(uw.y) * (acc[v][tb][3] + bs)); *(u32x2*)up = w; } } }
	v_mfma_f32_16x16x32_bf16 v[34:37], v[168:171], v[74:77], v[34:37]
	v_mfma_f32_16x16x32_bf16 v[168:171], v[172:175], v[74:77], v[38:41]
	s_nop 2
	ds_read_b128 v[38:41], v161 offset:35008
	ds_read_b128 v[172:175], v161 offset:39360
	ds_read_b128 v[74:77], v162 offset:192
	global_load_dword v156, v0, s[40:41]
	global_load_dword v203, v0, s[40:41] offset:64
	global_load_dword v204, v0, s[40:41] offset:128
	global_load_dword v205, v0, s[40:41] offset:192
	global_load_dword v206, v0, s[40:41] offset:256
	global_load_dword v207, v0, s[40:41] offset:320
	global_load_dword v208, v0, s[40:41] offset:384
	global_load_dword v209, v0, s[40:41] offset:448
	v_add_u32_e32 v200, s62, v134
	v_ashrrev_i32_e32 v201, 31, v200
	v_lshlrev_b64 v[200:201], 12, v[200:201]
	v_lshl_add_u64 v[200:201], v[132:133], 0, v[200:201]
	v_lshl_add_u64 v[200:201], v[200:201], 0, s[4:5]
	s_mov_b32 s98, 0x10000
	s_mov_b32 s99, 0
	global_load_dwordx2 v[214:215], v[200:201], off
	global_load_dwordx2 v[216:217], v[200:201], off offset:32
	v_lshl_add_u64 v[200:201], v[200:201], 0, s[98:99]
	global_load_dwordx2 v[218:219], v[200:201], off
	global_load_dwordx2 v[220:221], v[200:201], off offset:32
	v_lshl_add_u64 v[200:201], v[200:201], 0, s[98:99]
	global_load_dwordx2 v[222:223], v[200:201], off
	global_load_dwordx2 v[224:225], v[200:201], off offset:32
	v_lshl_add_u64 v[200:201], v[200:201], 0, s[98:99]
	global_load_dwordx2 v[226:227], v[200:201], off
	global_load_dwordx2 v[228:229], v[200:201], off offset:32
	v_lshl_add_u64 v[200:201], v[200:201], 0, s[98:99]
	global_load_dwordx2 v[230:231], v[200:201], off
	global_load_dwordx2 v[232:233], v[200:201], off offset:32
	v_lshl_add_u64 v[200:201], v[200:201], 0, s[98:99]
	global_load_dwordx2 v[234:235], v[200:201], off
	global_load_dwordx2 v[236:237], v[200:201], off offset:32
	v_lshl_add_u64 v[200:201], v[200:201], 0, s[98:99]
	global_load_dwordx2 v[238:239], v[200:201], off
	global_load_dwordx2 v[240:241], v[200:201], off offset:32
	v_lshl_add_u64 v[200:201], v[200:201], 0, s[98:99]
	global_load_dwordx2 v[242:243], v[200:201], off
	global_load_dwordx2 v[244:245], v[200:201], off offset:32
	s_waitcnt lgkmcnt(0)
	v_mfma_f32_16x16x32_bf16 v[90:93], v[172:175], v[74:77], v[42:45]
	s_nop 2
	ds_read_b128 v[42:45], v162 offset:4544
	s_waitcnt lgkmcnt(0)
	v_mfma_f32_16x16x32_bf16 v[86:89], v[38:41], v[42:45], v[54:57]
	s_waitcnt vmcnt(0)
	s_nop 0
	v_add_f32_e32 v90, v90, v156
	v_mfma_f32_16x16x32_bf16 v[82:85], v[172:175], v[42:45], v[50:53]
	ds_read_b128 v[42:45], v162 offset:8896
	v_add_f32_e32 v91, v91, v156
	v_add_f32_e32 v92, v92, v156
	v_mfma_f32_16x16x32_bf16 v[196:199], v[38:41], v[74:77], v[46:49]
	v_add_f32_e32 v93, v93, v156
	s_waitcnt lgkmcnt(0)
	v_mfma_f32_16x16x32_bf16 v[78:81], v[38:41], v[42:45], v[62:65]
	v_mfma_f32_16x16x32_bf16 v[74:77], v[172:175], v[42:45], v[58:61]
	ds_read_b128 v[42:45], v162 offset:13248
	s_nop 2
	v_add_f32_e32 v163, v196, v156
	s_waitcnt lgkmcnt(0)
	v_mfma_f32_16x16x32_bf16 v[70:73], v[38:41], v[42:45], v[70:73]
	v_mfma_f32_16x16x32_bf16 v[66:69], v[172:175], v[42:45], v[66:69]
	ds_read_b128 v[42:45], v162 offset:17600
	s_waitcnt lgkmcnt(0)
	v_mfma_f32_16x16x32_bf16 v[62:65], v[38:41], v[42:45], v[180:183]
	v_mfma_f32_16x16x32_bf16 v[58:61], v[172:175], v[42:45], v[176:179]
	ds_read_b128 v[42:45], v162 offset:21952
	s_waitcnt lgkmcnt(0)
	v_mfma_f32_16x16x32_bf16 v[54:57], v[38:41], v[42:45], v[184:187]
	v_mfma_f32_16x16x32_bf16 v[50:53], v[172:175], v[42:45], v[188:191]
	ds_read_b128 v[42:45], v162 offset:26304
	s_waitcnt lgkmcnt(0)
	v_mfma_f32_16x16x32_bf16 v[46:49], v[38:41], v[42:45], v[164:167]
	s_nop 2
	ds_read_b128 v[164:167], v162 offset:30656
	s_waitcnt lgkmcnt(0)
	v_mfma_f32_16x16x32_bf16 v[38:41], v[38:41], v[164:167], v[34:37]
	v_mfma_f32_16x16x32_bf16 v[34:37], v[172:175], v[164:167], v[168:171]
	v_add_u32_e32 v164, s62, v134
	v_ashrrev_i32_e32 v165, 31, v164
	v_lshlrev_b64 v[164:165], 12, v[164:165]
	v_lshl_add_u64 v[164:165], v[132:133], 0, v[164:165]
	v_lshl_add_u64 v[164:165], v[164:165], 0, s[4:5]
	v_mov_b32_e32 v166, v214
	v_mov_b32_e32 v167, v215
	v_mfma_f32_16x16x32_bf16 v[42:45], v[172:175], v[42:45], v[192:195]
	s_waitcnt vmcnt(0)
	v_lshlrev_b32_e32 v157, 16, v166
	v_mul_f32_e32 v157, v163, v157
	v_and_b32_e32 v163, 0xffff0000, v166
	v_add_f32_e32 v166, v197, v156
	v_mul_f32_e32 v163, v166, v163
	v_cvt_pk_bf16_f32 v166, v157, v163
	v_lshlrev_b32_e32 v157, 16, v167
	v_add_f32_e32 v163, v198, v156
	v_mul_f32_e32 v157, v163, v157
	v_and_b32_e32 v163, 0xffff0000, v167
	v_add_f32_e32 v167, v199, v156
	v_mul_f32_e32 v163, v167, v163
	v_cvt_pk_bf16_f32 v167, v157, v163
	global_store_dwordx2 v[164:165], v[166:167], off
	v_mov_b32_e32 v166, v216
	v_mov_b32_e32 v167, v217
	v_lshlrev_b32_e32 v157, 16, v166
	v_mul_f32_e32 v90, v90, v157
	v_and_b32_e32 v157, 0xffff0000, v166
	v_mul_f32_e32 v91, v91, v157
	v_cvt_pk_bf16_f32 v90, v90, v91
	v_lshlrev_b32_e32 v91, 16, v167
	v_mul_f32_e32 v91, v92, v91
	v_and_b32_e32 v92, 0xffff0000, v167
	v_mul_f32_e32 v92, v93, v92
	v_cvt_pk_bf16_f32 v91, v91, v92
	v_add_u32_e32 v92, s62, v144
	v_ashrrev_i32_e32 v93, 31, v92
	v_lshlrev_b64 v[92:93], 12, v[92:93]
	v_lshl_add_u64 v[92:93], v[132:133], 0, v[92:93]
	global_store_dwordx2 v[164:165], v[90:91], off offset:32
	v_lshl_add_u64 v[92:93], v[92:93], 0, s[4:5]
	v_lshl_add_u64 v[90:91], s[40:41], 0, v[0:1]
	v_mov_b32_e32 v0, v203
	v_add_f32_e32 v86, v86, v0
	v_mov_b32_e32 v164, v218
	v_mov_b32_e32 v165, v219
	v_add_f32_e32 v87, v87, v0
	v_add_f32_e32 v88, v88, v0
	v_add_f32_e32 v89, v89, v0
	v_add_f32_e32 v82, v82, v0
	v_add_f32_e32 v83, v83, v0
	v_add_f32_e32 v84, v84, v0
	v_add_f32_e32 v0, v85, v0
	v_lshlrev_b32_e32 v156, 16, v164
	v_mul_f32_e32 v86, v86, v156
	v_and_b32_e32 v156, 0xffff0000, v164
	v_mul_f32_e32 v87, v87, v156
	v_cvt_pk_bf16_f32 v86, v86, v87
	v_lshlrev_b32_e32 v87, 16, v165
	v_mul_f32_e32 v87, v88, v87
	v_and_b32_e32 v88, 0xffff0000, v165
	v_mul_f32_e32 v88, v89, v88
	v_cvt_pk_bf16_f32 v87, v87, v88
	global_store_dwordx2 v[92:93], v[86:87], off
	v_mov_b32_e32 v86, v220
	v_mov_b32_e32 v87, v221
	v_lshlrev_b32_e32 v88, 16, v86
	v_and_b32_e32 v86, 0xffff0000, v86
	v_mul_f32_e32 v82, v82, v88
	v_mul_f32_e32 v83, v83, v86
	v_cvt_pk_bf16_f32 v82, v82, v83
	v_lshlrev_b32_e32 v83, 16, v87
	v_mul_f32_e32 v83, v84, v83
	v_and_b32_e32 v84, 0xffff0000, v87
	v_mul_f32_e32 v0, v0, v84
	v_cvt_pk_bf16_f32 v83, v83, v0
	global_store_dwordx2 v[92:93], v[82:83], off offset:32
	s_and_saveexec_b64 s[4:5], vcc
	s_cbranch_execz .LBB0_1593
; __device__ __forceinline__ unsigned cvt_pk(float lo, float hi) { unsigned r; asm("v_cvt_pk_bf16_f32 %0, %1, %2" : "=v"(r) : "v"(lo), "v"(hi)); return r; }
; __device__ __forceinline__ float bflo(unsigned w) { return __uint_as_float(w << 16); }
; __device__ __forceinline__ float bfhi(unsigned w) { return __uint_as_float(w & 0xffff0000u); }
; __device__ __forceinline__ void spatial_phase(unsigned char* lds, const Params& p, int vb, int G, bool dry) {
;     ...
;         for (int tb = 0; tb < 8; ++tb) { const int t = 16 * tb + li;
;             if (t < L && !dry) { const float bs = p.in[16][g * 128 + t];
; #pragma unroll
;                 for (int v = 0; v < 2; ++v) { bf16_t* up = U + (size_t)(row0 + t) * D + g * 256 + 16 * (2 * wave + v) + 4 * fq; const u32x2 uw = *(const u32x2*)up;
;                     u32x2 w; w.x = cvt_pk(bflo(uw.x) * (acc[v][tb][0] + bs), bfhi(uw.x) * (acc[v][tb][1] + bs)); w.y = cvt_pk(bflo(uw.y) * (acc[v][tb][2] + bs), bfhi(uw.y) * (acc[v][tb][3] + bs)); *(u32x2*)up = w; } } }
	v_add_u32_e32 v82, s62, v145
	v_ashrrev_i32_e32 v83, 31, v82
	v_lshlrev_b64 v[82:83], 12, v[82:83]
	v_lshl_add_u64 v[82:83], v[132:133], 0, v[82:83]
	v_lshl_add_u64 v[82:83], s[38:39], 1, v[82:83]
	v_mov_b32_e32 v0, v204
	v_mov_b32_e32 v84, v222
	v_mov_b32_e32 v85, v223
	v_add_f32_e32 v78, v78, v0
	v_lshlrev_b32_e32 v86, 16, v84
	v_and_b32_e32 v84, 0xffff0000, v84
	v_add_f32_e32 v79, v79, v0
	v_mul_f32_e32 v78, v78, v86
	v_mul_f32_e32 v79, v79, v84
	v_cvt_pk_bf16_f32 v78, v78, v79
	v_lshlrev_b32_e32 v79, 16, v85
	v_add_f32_e32 v80, v80, v0
	v_mul_f32_e32 v79, v80, v79
	v_and_b32_e32 v80, 0xffff0000, v85
	v_add_f32_e32 v81, v81, v0
	v_mul_f32_e32 v80, v81, v80
	v_cvt_pk_bf16_f32 v79, v79, v80
	global_store_dwordx2 v[82:83], v[78:79], off
	v_mov_b32_e32 v78, v224
	v_mov_b32_e32 v79, v225
	v_add_f32_e32 v74, v74, v0
	v_add_f32_e32 v75, v75, v0
	v_add_f32_e32 v76, v76, v0
	v_add_f32_e32 v0, v77, v0
	v_lshlrev_b32_e32 v80, 16, v78
	v_and_b32_e32 v78, 0xffff0000, v78
	v_mul_f32_e32 v74, v74, v80
	v_mul_f32_e32 v75, v75, v78
	v_cvt_pk_bf16_f32 v74, v74, v75
	v_lshlrev_b32_e32 v75, 16, v79
	v_mul_f32_e32 v75, v76, v75
	v_and_b32_e32 v76, 0xffff0000, v79
	v_mul_f32_e32 v0, v0, v76
	v_cvt_pk_bf16_f32 v75, v75, v0
	global_store_dwordx2 v[82:83], v[74:75], off offset:32
	s_or_b64 exec, exec, s[4:5]
	v_cmp_gt_u32_e32 vcc, s63, v146
	s_and_saveexec_b64 s[4:5], vcc
	s_cbranch_execnz .LBB0_1594

; __device__ __forceinline__ unsigned cvt_pk(float lo, float hi) { unsigned r; asm("v_cvt_pk_bf16_f32 %0, %1, %2" : "=v"(r) : "v"(lo), "v"(hi)); return r; }
; __device__ __forceinline__ float bflo(unsigned w) { return __uint_as_float(w << 16); }
; __device__ __forceinline__ float bfhi(unsigned w) { return __uint_as_float(w & 0xffff0000u); }
; __device__ __forceinline__ void spatial_phase(unsigned char* lds, const Params& p, int vb, int G, bool dry) {
;     ...
;         for (int tb = 0; tb < 8; ++tb) { const int t = 16 * tb + li;
;             if (t < L && !dry) { const float bs = p.in[16][g * 128 + t];
; #pragma unroll
;                 for (int v = 0; v < 2; ++v) { bf16_t* up = U + (size_t)(row0 + t) * D + g * 256 + 16 * (2 * wave + v) + 4 * fq; const u32x2 uw = *(const u32x2*)up;
;                     u32x2 w; w.x = cvt_pk(bflo(uw.x) * (acc[v][tb][0] + bs), bfhi(uw.x) * (acc[v][tb][1] + bs)); w.y = cvt_pk(bflo(uw.y) * (acc[v][tb][2] + bs), bfhi(uw.y) * (acc[v][tb][3] + bs)); *(u32x2*)up = w; } } }
.LBB0_1590:
	v_add_u32_e32 v66, s62, v147
	v_ashrrev_i32_e32 v67, 31, v66
	v_lshlrev_b64 v[66:67], 12, v[66:67]
	v_lshl_add_u64 v[66:67], v[132:133], 0, v[66:67]
	v_lshl_add_u64 v[66:67], s[38:39], 1, v[66:67]
	v_mov_b32_e32 v0, v206
	v_mov_b32_e32 v68, v230
	v_mov_b32_e32 v69, v231
	v_add_f32_e32 v62, v62, v0
	v_lshlrev_b32_e32 v70, 16, v68
	v_and_b32_e32 v68, 0xffff0000, v68
	v_add_f32_e32 v63, v63, v0
	v_mul_f32_e32 v62, v62, v70
	v_mul_f32_e32 v63, v63, v68
	v_cvt_pk_bf16_f32 v62, v62, v63
	v_lshlrev_b32_e32 v63, 16, v69
	v_add_f32_e32 v64, v64, v0
	v_mul_f32_e32 v63, v64, v63
	v_and_b32_e32 v64, 0xffff0000, v69
	v_add_f32_e32 v65, v65, v0
	v_mul_f32_e32 v64, v65, v64
	v_cvt_pk_bf16_f32 v63, v63, v64
	global_store_dwordx2 v[66:67], v[62:63], off
	v_mov_b32_e32 v62, v232
	v_mov_b32_e32 v63, v233
	v_add_f32_e32 v58, v58, v0
	v_add_f32_e32 v59, v59, v0
	v_add_f32_e32 v60, v60, v0
	v_add_f32_e32 v0, v61, v0
	v_lshlrev_b32_e32 v64, 16, v62
	v_and_b32_e32 v62, 0xffff0000, v62
	v_mul_f32_e32 v58, v58, v64
	v_mul_f32_e32 v59, v59, v62
	v_cvt_pk_bf16_f32 v58, v58, v59
	v_lshlrev_b32_e32 v59, 16, v63
	v_mul_f32_e32 v59, v60, v59
	v_and_b32_e32 v60, 0xffff0000, v63
	v_mul_f32_e32 v0, v0, v60
	v_cvt_pk_bf16_f32 v59, v59, v0
	global_store_dwordx2 v[66:67], v[58:59], off offset:32
	s_or_b64 exec, exec, s[4:5]
	v_cmp_gt_u32_e32 vcc, s63, v148
	s_and_saveexec_b64 s[4:5], vcc
	s_cbranch_execnz .LBB0_1596

; __device__ __forceinline__ unsigned cvt_pk(float lo, float hi) { unsigned r; asm("v_cvt_pk_bf16_f32 %0, %1, %2" : "=v"(r) : "v"(lo), "v"(hi)); return r; }
; __device__ __forceinline__ float bflo(unsigned w) { return __uint_as_float(w << 16); }
; __device__ __forceinline__ float bfhi(unsigned w) { return __uint_as_float(w & 0xffff0000u); }
; __device__ __forceinline__ void spatial_phase(unsigned char* lds, const Params& p, int vb, int G, bool dry) {
;     ...
;         for (int tb = 0; tb < 8; ++tb) { const int t = 16 * tb + li;
;             if (t < L && !dry) { const float bs = p.in[16][g * 128 + t];
; #pragma unroll
;                 for (int v = 0; v < 2; ++v) { bf16_t* up = U + (size_t)(row0 + t) * D + g * 256 + 16 * (2 * wave + v) + 4 * fq; const u32x2 uw = *(const u32x2*)up;
;                     u32x2 w; w.x = cvt_pk(bflo(uw.x) * (acc[v][tb][0] + bs), bfhi(uw.x) * (acc[v][tb][1] + bs)); w.y = cvt_pk(bflo(uw.y) * (acc[v][tb][2] + bs), bfhi(uw.y) * (acc[v][tb][3] + bs)); *(u32x2*)up = w; } } }
.LBB0_1592:
	v_add_u32_e32 v50, s62, v149
	v_ashrrev_i32_e32 v51, 31, v50
	v_lshlrev_b64 v[50:51], 12, v[50:51]
	v_lshl_add_u64 v[50:51], v[132:133], 0, v[50:51]
	v_lshl_add_u64 v[50:51], s[38:39], 1, v[50:51]
	v_mov_b32_e32 v0, v208
	v_mov_b32_e32 v52, v238
	v_mov_b32_e32 v53, v239
	v_add_f32_e32 v46, v46, v0
	v_lshlrev_b32_e32 v54, 16, v52
	v_and_b32_e32 v52, 0xffff0000, v52
	v_add_f32_e32 v47, v47, v0
	v_mul_f32_e32 v46, v46, v54
	v_mul_f32_e32 v47, v47, v52
	v_cvt_pk_bf16_f32 v46, v46, v47
	v_lshlrev_b32_e32 v47, 16, v53
	v_add_f32_e32 v48, v48, v0
	v_mul_f32_e32 v47, v48, v47
	v_and_b32_e32 v48, 0xffff0000, v53
	v_add_f32_e32 v49, v49, v0
	v_mul_f32_e32 v48, v49, v48
	v_cvt_pk_bf16_f32 v47, v47, v48
	global_store_dwordx2 v[50:51], v[46:47], off
	v_mov_b32_e32 v46, v240
	v_mov_b32_e32 v47, v241
	v_add_f32_e32 v42, v42, v0
	v_add_f32_e32 v43, v43, v0
	v_add_f32_e32 v44, v44, v0
	v_add_f32_e32 v0, v45, v0
	v_lshlrev_b32_e32 v48, 16, v46
	v_and_b32_e32 v46, 0xffff0000, v46
	v_mul_f32_e32 v42, v42, v48
	v_mul_f32_e32 v43, v43, v46
	v_cvt_pk_bf16_f32 v42, v42, v43
	v_lshlrev_b32_e32 v43, 16, v47
	v_mul_f32_e32 v43, v44, v43
	v_and_b32_e32 v44, 0xffff0000, v47
	v_mul_f32_e32 v0, v0, v44
	v_cvt_pk_bf16_f32 v43, v43, v0
	global_store_dwordx2 v[50:51], v[42:43], off offset:32
	s_or_b64 exec, exec, s[4:5]
	v_cmp_gt_u32_e32 vcc, s63, v150
	s_and_saveexec_b64 s[4:5], vcc
	s_cbranch_execz .LBB0_1512
	s_branch .LBB0_1598

; __device__ __forceinline__ unsigned cvt_pk(float lo, float hi) { unsigned r; asm("v_cvt_pk_bf16_f32 %0, %1, %2" : "=v"(r) : "v"(lo), "v"(hi)); return r; }
; __device__ __forceinline__ float bflo(unsigned w) { return __uint_as_float(w << 16); }
; __device__ __forceinline__ float bfhi(unsigned w) { return __uint_as_float(w & 0xffff0000u); }
; __device__ __forceinline__ void spatial_phase(unsigned char* lds, const Params& p, int vb, int G, bool dry) {
;     ...
;         for (int tb = 0; tb < 8; ++tb) { const int t = 16 * tb + li;
;             if (t < L && !dry) { const float bs = p.in[16][g * 128 + t];
; #pragma unroll
;                 for (int v = 0; v < 2; ++v) { bf16_t* up = U + (size_t)(row0 + t) * D + g * 256 + 16 * (2 * wave + v) + 4 * fq; const u32x2 uw = *(const u32x2*)up;
;                     u32x2 w; w.x = cvt_pk(bflo(uw.x) * (acc[v][tb][0] + bs), bfhi(uw.x) * (acc[v][tb][1] + bs)); w.y = cvt_pk(bflo(uw.y) * (acc[v][tb][2] + bs), bfhi(uw.y) * (acc[v][tb][3] + bs)); *(u32x2*)up = w; } } }
.LBB0_1594:
	v_add_u32_e32 v74, s62, v146
	v_ashrrev_i32_e32 v75, 31, v74
	v_lshlrev_b64 v[74:75], 12, v[74:75]
	v_lshl_add_u64 v[74:75], v[132:133], 0, v[74:75]
	v_lshl_add_u64 v[74:75], s[38:39], 1, v[74:75]
	v_mov_b32_e32 v0, v205
	v_mov_b32_e32 v76, v226
	v_mov_b32_e32 v77, v227
	v_add_f32_e32 v70, v70, v0
	v_lshlrev_b32_e32 v78, 16, v76
	v_and_b32_e32 v76, 0xffff0000, v76
	v_add_f32_e32 v71, v71, v0
	v_mul_f32_e32 v70, v70, v78
	v_mul_f32_e32 v71, v71, v76
	v_cvt_pk_bf16_f32 v70, v70, v71
	v_lshlrev_b32_e32 v71, 16, v77
	v_add_f32_e32 v72, v72, v0
	v_mul_f32_e32 v71, v72, v71
	v_and_b32_e32 v72, 0xffff0000, v77
	v_add_f32_e32 v73, v73, v0
	v_mul_f32_e32 v72, v73, v72
	v_cvt_pk_bf16_f32 v71, v71, v72
	global_store_dwordx2 v[74:75], v[70:71], off
	v_mov_b32_e32 v70, v228
	v_mov_b32_e32 v71, v229
	v_add_f32_e32 v66, v66, v0
	v_add_f32_e32 v67, v67, v0
	v_add_f32_e32 v68, v68, v0
	v_add_f32_e32 v0, v69, v0
	v_lshlrev_b32_e32 v72, 16, v70
	v_and_b32_e32 v70, 0xffff0000, v70
	v_mul_f32_e32 v66, v66, v72
	v_mul_f32_e32 v67, v67, v70
	v_cvt_pk_bf16_f32 v66, v66, v67
	v_lshlrev_b32_e32 v67, 16, v71
	v_mul_f32_e32 v67, v68, v67
	v_and_b32_e32 v68, 0xffff0000, v71
	v_mul_f32_e32 v0, v0, v68
	v_cvt_pk_bf16_f32 v67, v67, v0
	global_store_dwordx2 v[74:75], v[66:67], off offset:32
	s_or_b64 exec, exec, s[4:5]
	v_cmp_gt_u32_e32 vcc, s63, v147
	s_and_saveexec_b64 s[4:5], vcc
	s_cbranch_execnz .LBB0_1590

; __device__ __forceinline__ unsigned cvt_pk(float lo, float hi) { unsigned r; asm("v_cvt_pk_bf16_f32 %0, %1, %2" : "=v"(r) : "v"(lo), "v"(hi)); return r; }
; __device__ __forceinline__ float bflo(unsigned w) { return __uint_as_float(w << 16); }
; __device__ __forceinline__ float bfhi(unsigned w) { return __uint_as_float(w & 0xffff0000u); }
; __device__ __forceinline__ void spatial_phase(unsigned char* lds, const Params& p, int vb, int G, bool dry) {
;     ...
;         for (int tb = 0; tb < 8; ++tb) { const int t = 16 * tb + li;
;             if (t < L && !dry) { const float bs = p.in[16][g * 128 + t];
; #pragma unroll
;                 for (int v = 0; v < 2; ++v) { bf16_t* up = U + (size_t)(row0 + t) * D + g * 256 + 16 * (2 * wave + v) + 4 * fq; const u32x2 uw = *(const u32x2*)up;
;                     u32x2 w; w.x = cvt_pk(bflo(uw.x) * (acc[v][tb][0] + bs), bfhi(uw.x) * (acc[v][tb][1] + bs)); w.y = cvt_pk(bflo(uw.y) * (acc[v][tb][2] + bs), bfhi(uw.y) * (acc[v][tb][3] + bs)); *(u32x2*)up = w; } } }
.LBB0_1596:
	v_add_u32_e32 v58, s62, v148
	v_ashrrev_i32_e32 v59, 31, v58
	v_lshlrev_b64 v[58:59], 12, v[58:59]
	v_lshl_add_u64 v[58:59], v[132:133], 0, v[58:59]
	v_lshl_add_u64 v[58:59], s[38:39], 1, v[58:59]
	v_mov_b32_e32 v0, v207
	v_mov_b32_e32 v60, v234
	v_mov_b32_e32 v61, v235
	v_add_f32_e32 v54, v54, v0
	v_lshlrev_b32_e32 v62, 16, v60
	v_and_b32_e32 v60, 0xffff0000, v60
	v_add_f32_e32 v55, v55, v0
	v_mul_f32_e32 v54, v54, v62
	v_mul_f32_e32 v55, v55, v60
	v_cvt_pk_bf16_f32 v54, v54, v55
	v_lshlrev_b32_e32 v55, 16, v61
	v_add_f32_e32 v56, v56, v0
	v_mul_f32_e32 v55, v56, v55
	v_and_b32_e32 v56, 0xffff0000, v61
	v_add_f32_e32 v57, v57, v0
	v_mul_f32_e32 v56, v57, v56
	v_cvt_pk_bf16_f32 v55, v55, v56
	global_store_dwordx2 v[58:59], v[54:55], off
	v_mov_b32_e32 v54, v236
	v_mov_b32_e32 v55, v237
	v_add_f32_e32 v50, v50, v0
	v_add_f32_e32 v51, v51, v0
	v_add_f32_e32 v52, v52, v0
	v_add_f32_e32 v0, v53, v0
	v_lshlrev_b32_e32 v56, 16, v54
	v_and_b32_e32 v54, 0xffff0000, v54
	v_mul_f32_e32 v50, v50, v56
	v_mul_f32_e32 v51, v51, v54
	v_cvt_pk_bf16_f32 v50, v50, v51
	v_lshlrev_b32_e32 v51, 16, v55
	v_mul_f32_e32 v51, v52, v51
	v_and_b32_e32 v52, 0xffff0000, v55
	v_mul_f32_e32 v0, v0, v52
	v_cvt_pk_bf16_f32 v51, v51, v0
	global_store_dwordx2 v[58:59], v[50:51], off offset:32
	s_or_b64 exec, exec, s[4:5]
	v_cmp_gt_u32_e32 vcc, s63, v149
	s_and_saveexec_b64 s[4:5], vcc
	s_cbranch_execnz .LBB0_1592

; __device__ __forceinline__ unsigned cvt_pk(float lo, float hi) { unsigned r; asm("v_cvt_pk_bf16_f32 %0, %1, %2" : "=v"(r) : "v"(lo), "v"(hi)); return r; }
; __device__ __forceinline__ float bflo(unsigned w) { return __uint_as_float(w << 16); }
; __device__ __forceinline__ float bfhi(unsigned w) { return __uint_as_float(w & 0xffff0000u); }
; __device__ __forceinline__ void spatial_phase(unsigned char* lds, const Params& p, int vb, int G, bool dry) {
;     ...
;         for (int tb = 0; tb < 8; ++tb) { const int t = 16 * tb + li;
;             if (t < L && !dry) { const float bs = p.in[16][g * 128 + t];
; #pragma unroll
;                 for (int v = 0; v < 2; ++v) { bf16_t* up = U + (size_t)(row0 + t) * D + g * 256 + 16 * (2 * wave + v) + 4 * fq; const u32x2 uw = *(const u32x2*)up;
;                     u32x2 w; w.x = cvt_pk(bflo(uw.x) * (acc[v][tb][0] + bs), bfhi(uw.x) * (acc[v][tb][1] + bs)); w.y = cvt_pk(bflo(uw.y) * (acc[v][tb][2] + bs), bfhi(uw.y) * (acc[v][tb][3] + bs)); *(u32x2*)up = w; } } }
.LBB0_1598:
	v_add_u32_e32 v42, s62, v150
	v_ashrrev_i32_e32 v43, 31, v42
	v_lshlrev_b64 v[42:43], 12, v[42:43]
	v_lshl_add_u64 v[42:43], v[132:133], 0, v[42:43]
	v_lshl_add_u64 v[42:43], s[38:39], 1, v[42:43]
	v_mov_b32_e32 v0, v209
	v_mov_b32_e32 v44, v242
	v_mov_b32_e32 v45, v243
	v_add_f32_e32 v38, v38, v0
	v_lshlrev_b32_e32 v46, 16, v44
	v_and_b32_e32 v44, 0xffff0000, v44
	v_add_f32_e32 v39, v39, v0
	v_mul_f32_e32 v38, v38, v46
	v_mul_f32_e32 v39, v39, v44
	v_cvt_pk_bf16_f32 v38, v38, v39
	v_lshlrev_b32_e32 v39, 16, v45
	v_add_f32_e32 v40, v40, v0
	v_mul_f32_e32 v39, v40, v39
	v_and_b32_e32 v40, 0xffff0000, v45
	v_add_f32_e32 v41, v41, v0
	v_mul_f32_e32 v40, v41, v40
	v_cvt_pk_bf16_f32 v39, v39, v40
	global_store_dwordx2 v[42:43], v[38:39], off
	v_mov_b32_e32 v38, v244
	v_mov_b32_e32 v39, v245
	v_add_f32_e32 v34, v34, v0
	v_add_f32_e32 v35, v35, v0
	v_add_f32_e32 v36, v36, v0
	v_add_f32_e32 v0, v37, v0
	v_lshlrev_b32_e32 v40, 16, v38
	v_and_b32_e32 v38, 0xffff0000, v38
	v_mul_f32_e32 v34, v34, v40
	v_mul_f32_e32 v35, v35, v38
	v_cvt_pk_bf16_f32 v34, v34, v35
	v_lshlrev_b32_e32 v35, 16, v39
	v_mul_f32_e32 v35, v36, v35
	v_and_b32_e32 v36, 0xffff0000, v39
	v_mul_f32_e32 v0, v0, v36
	v_cvt_pk_bf16_f32 v35, v35, v0
	global_store_dwordx2 v[42:43], v[34:35], off offset:32
	s_branch .LBB0_1512
